# gemm_out/gemm_pq layer 0: last (ragged, context-row) tile group spread over all 8 XCDs instead of 1-2
# baseline (speedup 1.0000x reference)
; DEV int xcd_tile_items(int mtiles, int NT) { const int groups = ((mtiles + 7) >> 3) * (NT >> 3); return ((groups + 7) >> 3) * 8 * 64; }
; DEV void phase_gemm_pq(const Params& p, int layer, int M, char* smem) {
;   EpiBf epi{layer ? WSP(bf16_t, L1_PQ) : WSP(bf16_t, R_PQ), 2048};
;   const bf16_t* Bt = WSP(bf16_t, S_WPQ) + (size_t)layer * 2048 * LDH;
;   const int items = xcd_tile_items(M / 128, 16);
;   for (int item = blockIdx.x; item < items; item += gridDim.x) {
;     int mt, nt;
;     if (!xcd_tile(item, M / 128, 16, mt, nt)) continue;
;     gemm_tile(WSP(bf16_t, OFF_H), LDH, Bt, LDH, 1024, mt * 128, nt * 128, epi, smem);
;   }
; }
.LBB0_644:
	s_cmp_eq_u32 s86, 0x200
	s_cbranch_scc0 .Lp8_norm
	s_cmpk_lt_i32 s11, 0x800
	s_cbranch_scc1 .Lp8_norm
	s_lshr_b32 s8, s51, 3
	s_cmp_lt_u32 s8, 8
	s_cbranch_scc0 .Lp8_inval
	s_lshr_b32 s9, s8, 1
	s_lshl_b32 s9, s9, 3
	s_and_b32 s12, s51, 7
	s_or_b32 s9, s9, s12
	s_add_i32 s9, s9, 256
	s_lshl_b32 s9, s9, 3
	s_and_b32 s8, s8, 1
	s_or_b32 s11, s9, s8
	s_branch .Lp8_set
.Lp8_inval:
	s_movk_i32 s11, 0x9ff
.Lp8_set:
	s_mov_b32 s10, s11

; DEV int xcd_tile_items(int mtiles, int NT) { const int groups = ((mtiles + 7) >> 3) * (NT >> 3); return ((groups + 7) >> 3) * 8 * 64; }
; DEV void phase_gemm_out(const Params& p, int layer, char* smem) {
;   float* X = WSP(float, OFF_X);
;   EpiRes epi;
;   epi.X = X; epi.mod = WSP(float, S_MOD) + (size_t)layer * 3 * 6144;
;   const bf16_t* A; const bf16_t* Bt; int M;
;   if (layer == 0) { epi.xin_main = p.in[I_X]; epi.xin_ctx = p.in[I_CTX]; A = WSP(bf16_t, R_MIX); Bt = WSP(bf16_t, S_WOUT0); M = MT; }
;   else { epi.xin_main = X; epi.xin_ctx = X + (size_t)MM * 1024; A = WSP(bf16_t, OFF_H); Bt = WSP(bf16_t, S_WHGOUT); M = MM; }
;   const int items = xcd_tile_items(M / 128, 8);
;   for (int item = blockIdx.x; item < items; item += gridDim.x) {
;     int mt, nt;
;     if (!xcd_tile(item, M / 128, 8, mt, nt)) continue;
;     gemm_tile(A, LDH, Bt, LDH, 1024, mt * 128, nt * 128, epi, smem);
;   }
; }
.LBB0_668:
	s_cmp_eq_u32 s86, 0x200
	s_cbranch_scc0 .Lp6_norm
	s_cmpk_lt_i32 s12, 0x400
	s_cbranch_scc1 .Lp6_norm
	s_lshr_b32 s8, s51, 3
	s_cmp_lt_u32 s8, 4
	s_cbranch_scc0 .Lp6_inval
	s_lshl_b32 s8, s8, 3
	s_and_b32 s9, s51, 7
	s_or_b32 s8, s8, s9
	s_add_i32 s8, s8, 128
	s_lshl_b32 s12, s8, 3
	s_branch .Lp6_set
.Lp6_inval:
	s_movk_i32 s12, 0x5ff
.Lp6_set:
	s_mov_b32 s10, s12
	s_lshl_b32 s11, s12, 4
